# second co-resident block delayed by one s_sleep 127 (~4us, one tile boundary) at GU and PROJ phase start so tile epilogues of the two blocks do not coincide
# baseline (speedup 1.0000x reference)
.LBB0_211:
	s_or_b64 exec, exec, s[0:1]
	v_readlane_b32 s2, v254, 41
	v_readlane_b32 s3, v254, 42
	v_readlane_b32 s0, v253, 0
	s_mov_b32 s3, s97
	s_waitcnt lgkmcnt(0)
	s_barrier
	s_getreg_b32 s100, hwreg(HW_REG_LDS_ALLOC, 0, 8)
	s_cmp_eq_u32 s100, 0
	s_cbranch_scc1 .Lstag_211_done
	s_sleep 127
.Lstag_211_done:
	s_ashr_i32 s8, s0, 3
	v_writelane_b32 v254, s2, 41
	s_cmpk_gt_i32 s8, 0x197
	s_nop 0
	v_writelane_b32 v254, s3, 42
	s_cbranch_scc1 .LBB0_351
	v_readlane_b32 s12, v253, 36
	v_readlane_b32 s13, v253, 37
	v_readlane_b32 s14, v253, 38
	v_readlane_b32 s15, v253, 39
	v_readlane_b32 s16, v253, 40
	v_readlane_b32 s17, v253, 41
	v_readlane_b32 s18, v253, 42
	v_readlane_b32 s19, v253, 43
	v_readlane_b32 s20, v253, 44
	v_readlane_b32 s21, v253, 45
	v_readlane_b32 s2, v254, 41
	v_readlane_b32 s22, v253, 46
	v_readlane_b32 s23, v253, 47
	v_readlane_b32 s24, v253, 48
	v_readlane_b32 s25, v253, 49
	v_readlane_b32 s26, v253, 50
	v_readlane_b32 s27, v253, 51
	s_mov_b64 s[12:13], s[20:21]
	s_mul_i32 s1, s2, 0x600000
	s_mov_b64 s[16:17], s[24:25]
	s_add_u32 s9, s16, s1
	s_addc_u32 s10, s17, 0
	s_and_b32 s11, s0, 7
	s_mul_i32 s11, s11, 17
	v_readlane_b32 s3, v254, 42
	s_mov_b64 s[14:15], s[22:23]
	s_mov_b64 s[18:19], s[26:27]
	s_branch .LBB0_215

.LBB0_1029:
	s_or_b64 exec, exec, s[0:1]
	v_readlane_b32 s0, v253, 0
	s_waitcnt lgkmcnt(0)
	s_barrier
	s_getreg_b32 s100, hwreg(HW_REG_LDS_ALLOC, 0, 8)
	s_cmp_eq_u32 s100, 0
	s_cbranch_scc1 .Lstag_1029_done
	s_sleep 127
